# k5 plus scan-phase rebalancing: the Fourier-output transposition tiles go to the GLA workgroups only (16 each), none to the longer-running mLSTM workgroups
# speedup vs baseline: 1.0043x; 1.0033x over previous
.LBB0_1865:
	s_mov_b32 s98, s2
	s_mov_b32 s99, s24
	s_cmp_lt_i32 s96, 7
	s_cselect_b64 s[12:13], -1, 0
	s_and_b64 s[0:1], s[12:13], s[4:5]
	s_andn2_b64 vcc, exec, s[0:1]
	s_cbranch_vccnz .LBB0_1939
	s_bitcmp0_b32 s2, 3
	s_cselect_b64 s[20:21], -1, 0
	s_cmpk_lg_i32 s99, 0x100
	s_cbranch_scc1 .Ltr_done_0a
	s_bitcmp1_b32 s98, 2
	s_cbranch_scc1 .Ltr_gla_0a
	s_movk_i32 s2, 0x800
	s_branch .Ltr_str_0a
.Ltr_gla_0a:
	s_lshr_b32 s100, s98, 1
	s_and_b32 s100, s100, 0x70
	s_and_b32 s2, s98, 11
	s_or_b32 s2, s2, s100
	s_lshr_b32 s100, s98, 2
	s_and_b32 s100, s100, 4
	s_or_b32 s2, s2, s100
.Ltr_str_0a:
	s_movk_i32 s24, 0x80
.Ltr_done_0a:
	s_lshl_b32 s10, s2, 2
	s_and_b32 s18, s10, 0xffffffc0
	s_lshl_b32 s3, s2, 6
	s_ashr_i32 s19, s18, 31
	s_cmpk_lt_i32 s2, 0x800
	s_cselect_b64 s[0:1], -1, 0
	s_add_i32 s4, 0, 0x255a8
	v_mov_b32_e32 v1, s4
	s_add_i32 s4, 0, 0x255d8
	s_waitcnt vmcnt(0)
	ds_read2_b64 v[2:5], v1 offset1:1
	v_mov_b32_e32 v1, s4
	ds_read2_b64 v[6:9], v1 offset1:1
	s_add_i32 s4, 0, 0x255e8
	v_mov_b32_e32 v1, s4
	s_add_i32 s4, 0, 0x255f8
	s_waitcnt lgkmcnt(1)
	v_readfirstlane_b32 s15, v3
	v_readfirstlane_b32 s14, v2
	v_readfirstlane_b32 s17, v5
	v_readfirstlane_b32 s16, v4
	ds_read2_b64 v[2:5], v1 offset1:1
	v_mov_b32_e32 v1, s4
	s_waitcnt lgkmcnt(1)
	v_readfirstlane_b32 s23, v7
	v_readfirstlane_b32 s22, v6
	v_readfirstlane_b32 s27, v9
	v_readfirstlane_b32 s26, v8
	ds_read2_b64 v[6:9], v1 offset1:1
	s_add_i32 s4, 0, 0x25608
	v_mov_b32_e32 v1, s4
	s_add_i32 s4, 0, 0x25670
	s_waitcnt lgkmcnt(1)
	v_readfirstlane_b32 s11, v3
	v_readfirstlane_b32 s25, v2
	v_readfirstlane_b32 s30, v5
	v_readfirstlane_b32 s31, v4
	ds_read2_b64 v[2:5], v1 offset1:1
	v_mov_b32_e32 v1, s4
	s_waitcnt lgkmcnt(1)
	v_readfirstlane_b32 s33, v7
	v_readfirstlane_b32 s50, v6
	v_readfirstlane_b32 s51, v9
	v_readfirstlane_b32 s52, v8
	ds_read_b128 v[6:9], v1
	s_add_i32 s4, 0, 0x25680
	v_mov_b32_e32 v1, s4
	s_add_i32 s4, 0, 0x25690
	s_waitcnt lgkmcnt(1)
	v_readfirstlane_b32 s53, v3
	v_readfirstlane_b32 s54, v2
	v_readfirstlane_b32 s55, v5
	v_readfirstlane_b32 s56, v4
	ds_read_b128 v[2:5], v1
	v_mov_b32_e32 v1, s4
	s_waitcnt lgkmcnt(1)
	v_readfirstlane_b32 s35, v7
	v_readfirstlane_b32 s34, v6
	ds_read_b64 v[6:7], v1
	v_cndmask_b32_e64 v1, 0, 1, s[0:1]
	v_readfirstlane_b32 s37, v9
	v_readfirstlane_b32 s36, v8
	s_waitcnt lgkmcnt(1)
	v_readfirstlane_b32 s39, v3
	v_readfirstlane_b32 s38, v2
	v_readfirstlane_b32 s57, v5
	v_readfirstlane_b32 s58, v4
	s_waitcnt lgkmcnt(0)
	v_readfirstlane_b32 s59, v7
	v_readfirstlane_b32 s60, v6
	s_and_b64 vcc, exec, s[20:21]
	v_cmp_ne_u32_e64 s[4:5], 1, v1
	s_cbranch_vccnz .LBB0_1875
	v_mov_b32_e32 v1, v0
	s_and_b64 vcc, exec, s[4:5]
	s_cbranch_vccnz .LBB0_1874
	v_add_u32_e32 v6, 0x200, v1
	s_and_b32 s6, s3, 0x3c0
	v_lshlrev_b32_e32 v2, 2, v1
	s_lshl_b64 s[0:1], s[18:19], 1
	v_ashrrev_i32_e32 v9, 4, v1
	v_ashrrev_i32_e32 v14, 4, v6
	v_and_b32_e32 v8, 60, v2
	s_add_u32 s0, s16, s0
	v_add_u32_e32 v4, s6, v9
	v_add_u32_e32 v6, s6, v14
	s_addc_u32 s1, s17, s1
	v_lshlrev_b32_e32 v10, 1, v8
	v_mov_b32_e32 v11, 0
	v_ashrrev_i32_e32 v5, 31, v4
	v_ashrrev_i32_e32 v7, 31, v6
	v_lshl_add_u64 v[2:3], s[0:1], 0, v[10:11]
	v_lshlrev_b64 v[4:5], 14, v[4:5]
	v_lshlrev_b64 v[6:7], 14, v[6:7]
	v_lshl_add_u64 v[4:5], v[2:3], 0, v[4:5]
	v_lshl_add_u64 v[2:3], v[2:3], 0, v[6:7]
	global_load_dwordx2 v[4:5], v[4:5], off
	v_ashrrev_i32_e32 v15, 3, v1
	global_load_dwordx2 v[20:21], v[2:3], off
	v_lshlrev_b32_e32 v1, 3, v1
	s_movk_i32 s6, 0x104
	v_and_b32_e32 v2, 56, v1
	v_lshl_add_u32 v1, v15, 2, 0
	v_mul_lo_u32 v3, v9, s6
	v_lshl_add_u32 v6, v8, 2, 0
	v_mul_u32_u24_e32 v7, 0x104, v2
	v_mul_lo_u32 v8, v14, s6
	s_mov_b32 s28, 0xffff0000
	s_mov_b32 s1, 0
	s_movk_i32 s29, 0x7fff
	s_mov_b32 s0, s3
	s_mov_b32 s46, s10
	s_lshl_b32 s40, s24, 2
	s_lshl_b32 s41, s24, 6
	v_lshl_add_u64 v[12:13], s[16:17], 0, v[10:11]
	v_add_u32_e32 v16, v6, v3
	v_add_u32_e32 v17, v6, v8
	v_add_u32_e32 v18, v1, v7
	v_lshlrev_b32_e32 v10, 1, v2
	s_mov_b32 s44, s2
	s_waitcnt vmcnt(1)
	v_lshlrev_b32_e32 v2, 16, v4
	v_and_b32_e32 v1, 0xffff0000, v4
	v_lshlrev_b32_e32 v4, 16, v5
	v_and_b32_e32 v3, 0xffff0000, v5
	s_waitcnt vmcnt(0)
	v_lshlrev_b32_e32 v6, 16, v20
	v_and_b32_e32 v5, 0xffff0000, v20
	v_lshlrev_b32_e32 v8, 16, v21
	v_and_b32_e32 v7, 0xffff0000, v21
	s_branch .LBB0_1870

.LBB0_1875:
	s_mov_b32 s2, s98
	s_mov_b32 s24, s99
	s_cmpk_gt_i32 s2, 0xff
	s_cbranch_scc1 .LBB0_1930
	v_mbcnt_lo_u32_b32 v2, -1, 0
	s_movk_i32 s61, 0xff80
	s_mov_b32 s41, 0
	v_mov_b32_e32 v3, 0
	s_movk_i32 s62, 0x100
	s_movk_i32 s63, 0x80
	s_movk_i32 s64, 0x90
	s_movk_i32 s65, 0x110
	s_movk_i32 s66, 0x7fff
	s_mov_b32 s67, 0xffff0000
	s_add_i32 s68, 0, 0x13800
	s_add_i32 s69, 0, 0x1aa00
	s_add_i32 s70, 0, 0x1ae00
	s_add_i32 s71, 0, 0x14a00
	s_movk_i32 s72, 0x210
	s_movk_i32 s73, 0xfe80
	s_movk_i32 s74, 0x1800
	s_mov_b32 s75, 0x5040100
	v_mov_b32_e32 v1, 0x3f80
	v_mbcnt_hi_u32_b32 v118, -1, v2
	s_mov_b32 s76, s2
	s_branch .LBB0_1879

.LBB0_1930:
	s_cmpk_lg_i32 s99, 0x100
	s_cbranch_scc1 .Ltr_done_0b
	s_bitcmp1_b32 s98, 2
	s_cbranch_scc1 .Ltr_gla_0b
	s_movk_i32 s2, 0x800
	s_branch .Ltr_str_0b

.LBB0_1939:
	s_mov_b32 s2, s98
	s_mov_b32 s24, s99
	s_cmp_gt_i32 s97, 7
	s_cselect_b64 s[0:1], -1, 0
	s_and_b64 s[4:5], s[12:13], s[0:1]
	s_andn2_b64 vcc, exec, s[4:5]
	s_cbranch_vccnz .LBB0_1993
	s_waitcnt vmcnt(0)
	s_barrier
	s_mov_b64 s[4:5], exec
	v_readlane_b32 s6, v238, 2
	v_readlane_b32 s7, v238, 3
	s_and_b64 s[6:7], s[4:5], s[6:7]
	s_mov_b64 exec, s[6:7]
	s_cbranch_execz .LBB0_1992
	s_add_i32 s3, 0, 0x25480
	v_mov_b32_e32 v1, s3
	s_waitcnt vmcnt(0) expcnt(0) lgkmcnt(0)
	ds_read_b32 v3, v1
	s_add_i32 s3, 0, 0x25484
	v_mov_b32_e32 v1, s3
	ds_read_b32 v1, v1
	s_waitcnt lgkmcnt(1)
	v_cmp_ne_u32_e32 vcc, 0, v3
	s_cbranch_vccnz .LBB0_1956
	v_readlane_b32 s6, v238, 0
	v_readlane_b32 s7, v238, 1
	s_load_dwordx2 s[10:11], s[6:7], 0x4
	s_add_u32 s6, s42, 0x1000
	s_addc_u32 s7, s43, 0
	s_add_u32 s8, s42, 0x1100
	s_addc_u32 s9, s43, 0
	s_add_u32 s12, s42, 0x1200
	s_addc_u32 s13, s43, 0
	s_waitcnt lgkmcnt(0)
	s_mul_i32 s3, s10, s24
	s_add_u32 s14, s42, 0x1300
	s_mul_i32 s3, s3, s11
	s_addc_u32 s15, s43, 0
	s_mov_b32 s10, 1
	v_mov_b32_e32 v17, 0
	s_branch .LBB0_1944

.LBB0_3902:
	s_mov_b32 s98, s2
	s_mov_b32 s99, s24
	s_cmp_lt_i32 s96, 14
	s_cselect_b64 s[12:13], -1, 0
	s_and_b64 s[0:1], s[12:13], s[4:5]
	s_andn2_b64 vcc, exec, s[0:1]
	s_cbranch_vccnz .LBB0_3976
	s_bitcmp0_b32 s2, 3
	s_cselect_b64 s[20:21], -1, 0
	s_cmpk_lg_i32 s99, 0x100
	s_cbranch_scc1 .Ltr_done_1a
	s_bitcmp1_b32 s98, 2
	s_cbranch_scc1 .Ltr_gla_1a
	s_movk_i32 s2, 0x800
	s_branch .Ltr_str_1a

.LBB0_3976:
	s_mov_b32 s2, s98
	s_mov_b32 s24, s99
	s_cmp_gt_i32 s97, 14
	s_cselect_b64 s[0:1], -1, 0
	s_and_b64 s[4:5], s[12:13], s[0:1]
	s_andn2_b64 vcc, exec, s[4:5]
	s_cbranch_vccnz .LBB0_4030
	s_waitcnt vmcnt(0)
	s_barrier
	s_mov_b64 s[4:5], exec
	v_readlane_b32 s6, v238, 2
	v_readlane_b32 s7, v238, 3
	s_and_b64 s[6:7], s[4:5], s[6:7]
	s_mov_b64 exec, s[6:7]
	s_cbranch_execz .LBB0_4029
	s_add_i32 s3, 0, 0x25480
	v_mov_b32_e32 v1, s3
	s_waitcnt vmcnt(0) expcnt(0) lgkmcnt(0)
	ds_read_b32 v3, v1
	s_add_i32 s3, 0, 0x25484
	v_mov_b32_e32 v1, s3
	ds_read_b32 v1, v1
	s_waitcnt lgkmcnt(1)
	v_cmp_ne_u32_e32 vcc, 0, v3
	s_cbranch_vccnz .LBB0_3993
	v_readlane_b32 s6, v238, 0
	v_readlane_b32 s7, v238, 1
	s_load_dwordx2 s[10:11], s[6:7], 0x4
	s_add_u32 s6, s42, 0x1000
	s_addc_u32 s7, s43, 0
	s_add_u32 s8, s42, 0x1100
	s_addc_u32 s9, s43, 0
	s_add_u32 s12, s42, 0x1200
	s_addc_u32 s13, s43, 0
	s_waitcnt lgkmcnt(0)
	s_mul_i32 s3, s10, s24
	s_add_u32 s14, s42, 0x1300
	s_mul_i32 s3, s3, s11
	s_addc_u32 s15, s43, 0
	s_mov_b32 s10, 1
	v_mov_b32_e32 v17, 0
	s_branch .LBB0_3981
